# attention loop: late softmax exps done in place and row-sum add chain moved into QK MFMA gaps (acc in v251), K/V LDS writes issued before the trailing exps; bit-identical output
# speedup vs baseline: 1.0018x; 1.0018x over previous
; __device__ __forceinline__ void finishSM(f32x16& p0, f32x16& p1, float alpha, float& l_reg, bf16x8& pa0, bf16x8& pa1, bf16x8& pa2, bf16x8& pa3) {
; #pragma unroll
;   for (int r = 0; r < 16; ++r) p1[r] = __builtin_amdgcn_exp2f(p1[r]);
;   float ps = 0;
; #pragma unroll
;   for (int r = 0; r < 16; ++r) ps += p0[r];
; #pragma unroll
;   for (int r = 0; r < 16; ++r) ps += p1[r];
;   { auto rr = __builtin_amdgcn_permlane32_swap(__float_as_uint(ps), __float_as_uint(ps), false, false);
; __device__ __forceinline__ void qkt(f32x16& p0, f32x16& p1, const char* Kn, const char* Kr, const char* Qr, const bf16x8* qr, const f32x16& negm, int lane) {
;   const int kn = (int)(uintptr_t)Kn + (lane & 31) * 16 + (lane >> 5) * 1024, kr = (int)(uintptr_t)Kr + (lane & 31) * 16 + (lane >> 5) * 1024, qa = (int)(uintptr_t)Qr + lane * 16;
;   bf16x8 a0, a1, b0, b1, qa_, qb_;
;     ...
;   a0 = dsr128<0 * 2048>(kn); a1 = dsr128<0 * 2048 + 512>(kn);
;   b0 = dsr128<1 * 2048>(kn); b1 = dsr128<1 * 2048 + 512>(kn); LGKM_W2(2, a0, a1);
;   p0 = __builtin_amdgcn_mfma_f32_32x32x16_bf16(a0, qr[0], negm, 0, 0, 0); p1 = __builtin_amdgcn_mfma_f32_32x32x16_bf16(a1, qr[0], negm, 0, 0, 0);
;   a0 = dsr128<2 * 2048>(kn); a1 = dsr128<2 * 2048 + 512>(kn); LGKM_W2(2, b0, b1); MM(b0, b1, qr[1]);
;   b0 = dsr128<3 * 2048>(kn); b1 = dsr128<3 * 2048 + 512>(kn); LGKM_W2(2, a0, a1); MM(a0, a1, qr[2]);
;   a0 = dsr128<4 * 2048>(kn); a1 = dsr128<4 * 2048 + 512>(kn); LGKM_W2(2, b0, b1); MM(b0, b1, qr[3]);
;   b0 = dsr128<5 * 2048>(kn); b1 = dsr128<5 * 2048 + 512>(kn); LGKM_W2(2, a0, a1); MM(a0, a1, qr[4]);
;   a0 = dsr128<6 * 2048>(kn); a1 = dsr128<6 * 2048 + 512>(kn); LGKM_W2(2, b0, b1); MM(b0, b1, qr[5]);
;   b0 = dsr128<7 * 2048>(kn); b1 = dsr128<7 * 2048 + 512>(kn); LGKM_W2(2, a0, a1); MM(a0, a1, qr[6]);
;   a0 = dsr128<0 * 2048>(kr); a1 = dsr128<0 * 2048 + 512>(kr); qa_ = dsr128<0 * 1024>(qa); LGKM_W2(3, b0, b1); MM(b0, b1, qr[7]);
;   b0 = dsr128<1 * 2048>(kr); b1 = dsr128<1 * 2048 + 512>(kr); qb_ = dsr128<1 * 1024>(qa); LGKM_W3(3, a0, a1, qa_); MM(a0, a1, qa_);
;   a0 = dsr128<2 * 2048>(kr); a1 = dsr128<2 * 2048 + 512>(kr); qa_ = dsr128<2 * 1024>(qa); LGKM_W3(3, b0, b1, qb_); MM(b0, b1, qb_);
;   b0 = dsr128<3 * 2048>(kr); b1 = dsr128<3 * 2048 + 512>(kr); qb_ = dsr128<3 * 1024>(qa); LGKM_W3(3, a0, a1, qa_); MM(a0, a1, qa_);
;   LGKM_W3(0, b0, b1, qb_); MM(b0, b1, qb_);
.LBB0_558:
	ds_read_b128 v[98:101], v204 offset:0
	ds_read_b128 v[178:181], v204 offset:0x200
	ds_read_b128 v[210:213], v204 offset:0x800
	ds_read_b128 v[214:217], v204 offset:0xa00
	v_exp_f32_e32 v82, v82
	s_waitcnt lgkmcnt(2)
	v_exp_f32_e32 v83, v83
	v_mfma_f32_32x32x16_bf16 v[114:129], v[98:101], v[130:133], v[66:81]
	v_exp_f32_e32 v84, v84
	v_exp_f32_e32 v85, v85
	v_exp_f32_e32 v86, v86
	v_exp_f32_e32 v87, v87
	v_exp_f32_e32 v88, v88
	v_exp_f32_e32 v89, v89
	v_mfma_f32_32x32x16_bf16 v[98:113], v[178:181], v[130:133], v[66:81]
	v_exp_f32_e32 v90, v90
	v_add_f32_e32 v251, 0, v172
	v_add_f32_e32 v251, v175, v251
	ds_read_b128 v[178:181], v204 offset:0x1000
	ds_read_b128 v[218:221], v204 offset:0x1200
	s_waitcnt lgkmcnt(2)
	s_nop 0
	v_mfma_f32_32x32x16_bf16 v[114:129], v[210:213], v[134:137], v[114:129]
	v_add_f32_e32 v251, v173, v251
	v_exp_f32_e32 v91, v91
	v_add_f32_e32 v251, v176, v251
	ds_read_b128 v[210:213], v204 offset:0x1800
	v_mfma_f32_32x32x16_bf16 v[98:113], v[214:217], v[134:137], v[98:113]
	v_add_f32_e32 v251, v174, v251
	v_add_f32_e32 v251, v177, v251
	v_exp_f32_e32 v92, v92
	ds_read_b128 v[214:217], v204 offset:0x1a00
	s_waitcnt lgkmcnt(2)
	s_nop 0
	v_mfma_f32_32x32x16_bf16 v[114:129], v[178:181], v[138:141], v[114:129]
	v_add_f32_e32 v251, v170, v251
	v_add_f32_e32 v251, v171, v251
	v_add_f32_e32 v251, v166, v251
	ds_read_b128 v[178:181], v204 offset:0x2000
	v_mfma_f32_32x32x16_bf16 v[98:113], v[218:221], v[138:141], v[98:113]
	v_exp_f32_e32 v93, v93
	v_add_f32_e32 v251, v168, v251
	v_add_f32_e32 v251, v167, v251
	ds_read_b128 v[218:221], v204 offset:0x2200
	s_waitcnt lgkmcnt(2)
	s_nop 0
	v_mfma_f32_32x32x16_bf16 v[114:129], v[210:213], v[142:145], v[114:129]
	v_add_f32_e32 v251, v169, v251
	v_exp_f32_e32 v94, v94
	v_add_f32_e32 v251, v162, v251
	ds_read_b128 v[210:213], v204 offset:0x2800
	v_mfma_f32_32x32x16_bf16 v[98:113], v[214:217], v[142:145], v[98:113]
	v_add_f32_e32 v251, v164, v251
	v_add_f32_e32 v251, v163, v251
	v_exp_f32_e32 v95, v95
	ds_read_b128 v[214:217], v204 offset:0x2a00
	s_waitcnt lgkmcnt(2)
	s_nop 0
	v_mfma_f32_32x32x16_bf16 v[114:129], v[178:181], v[146:149], v[114:129]
	v_add_f32_e32 v251, v165, v251
	v_add_f32_e32 v251, v82, v251
	v_add_f32_e32 v251, v83, v251
	ds_read_b128 v[178:181], v204 offset:0x3000
	v_mfma_f32_32x32x16_bf16 v[98:113], v[218:221], v[146:149], v[98:113]
	v_exp_f32_e32 v96, v96
	v_add_f32_e32 v251, v84, v251
	v_add_f32_e32 v251, v85, v251
	ds_read_b128 v[218:221], v204 offset:0x3200
	s_waitcnt lgkmcnt(2)
	s_nop 0
	v_mfma_f32_32x32x16_bf16 v[114:129], v[210:213], v[150:153], v[114:129]
	v_add_f32_e32 v251, v86, v251
	v_exp_f32_e32 v97, v97
	v_add_f32_e32 v251, v87, v251
	ds_read_b128 v[210:213], v204 offset:0x3800
	v_mfma_f32_32x32x16_bf16 v[98:113], v[214:217], v[150:153], v[98:113]
	v_add_f32_e32 v251, v88, v251
	v_add_f32_e32 v251, v89, v251
	v_add_f32_e32 v251, v90, v251
	v_add_f32_e32 v251, v91, v251
	ds_read_b128 v[214:217], v204 offset:0x3a00
	s_waitcnt lgkmcnt(2)
	s_nop 0
	v_mfma_f32_32x32x16_bf16 v[114:129], v[178:181], v[154:157], v[114:129]
	v_add_f32_e32 v251, v92, v251
	v_add_f32_e32 v251, v93, v251
	v_add_f32_e32 v251, v94, v251
	v_add_f32_e32 v251, v95, v251
	ds_read_b128 v[178:181], v205 offset:0
	v_mfma_f32_32x32x16_bf16 v[98:113], v[218:221], v[154:157], v[98:113]
	v_add_f32_e32 v251, v96, v251
	v_add_f32_e32 v251, v97, v251
	ds_read_b128 v[218:221], v205 offset:0x200
	ds_read_b128 v[222:225], v189 offset:0
	s_waitcnt lgkmcnt(3)
	s_nop 0
	v_mfma_f32_32x32x16_bf16 v[114:129], v[210:213], v[158:161], v[114:129]
	ds_read_b128 v[210:213], v205 offset:0x800
	v_mfma_f32_32x32x16_bf16 v[98:113], v[214:217], v[158:161], v[98:113]
	ds_read_b128 v[214:217], v205 offset:0xa00
	ds_read_b128 v[226:229], v189 offset:0x400
	s_waitcnt lgkmcnt(3)
	s_nop 0
	v_mfma_f32_32x32x16_bf16 v[114:129], v[178:181], v[222:225], v[114:129]
	ds_read_b128 v[178:181], v205 offset:0x1000
	v_mfma_f32_32x32x16_bf16 v[98:113], v[218:221], v[222:225], v[98:113]
	ds_read_b128 v[218:221], v205 offset:0x1200
	ds_read_b128 v[222:225], v189 offset:0x800
	s_waitcnt lgkmcnt(3)
	s_nop 0
	v_mfma_f32_32x32x16_bf16 v[114:129], v[210:213], v[226:229], v[114:129]
	ds_read_b128 v[210:213], v205 offset:0x1800
	v_mfma_f32_32x32x16_bf16 v[98:113], v[214:217], v[226:229], v[98:113]
	ds_read_b128 v[214:217], v205 offset:0x1a00
	ds_read_b128 v[226:229], v189 offset:0xc00
	s_waitcnt lgkmcnt(3)
	s_nop 0
	s_waitcnt lgkmcnt(0)
; #define PV_WAIT(n, f) asm volatile("s_waitcnt lgkmcnt(" #n ")" : "+v"(f.l0), "+v"(f.h0), "+v"(f.l1), "+v"(f.h1), "+v"(f.l2), "+v"(f.h2), "+v"(f.l3), "+v"(f.h3) :: "memory")
; __device__ __forceinline__ void finishSM(f32x16& p0, f32x16& p1, float alpha, float& l_reg, bf16x8& pa0, bf16x8& pa1, bf16x8& pa2, bf16x8& pa3) {
;     ...
;   PK4(p0, 0, pa0); PK4(p0, 8, pa1); PK4(p1, 0, pa2); PK4(p1, 8, pa3);
; __device__ __forceinline__ void pv_d0(f32x16* o, int vb, bf16x8 pa0, bf16x8 pa1, bf16x8 pa2, bf16x8 pa3) {
;   VF fa, fb;
;   pv_rd<0>(fa, vb);
;   pv_rd<1>(fb, vb); PV_WAIT(8, fa); pv_mm(o[0], fa, pa0, pa1, pa2, pa3);
;   pv_rd<2>(fa, vb); PV_WAIT(8, fb); pv_mm(o[1], fb, pa0, pa1, pa2, pa3);
;   pv_rd<3>(fb, vb); PV_WAIT(8, fa); pv_mm(o[2], fa, pa0, pa1, pa2, pa3);
;   PV_WAIT(0, fb); pv_mm(o[3], fb, pa0, pa1, pa2, pa3);
; }
	v_mfma_f32_32x32x16_bf16 v[114:129], v[178:181], v[222:225], v[114:129]
	v_cvt_pk_bf16_f32 v178, v90, v91
	v_cvt_pk_bf16_f32 v179, v92, v93
	v_cvt_pk_bf16_f32 v180, v94, v95
	v_cvt_pk_bf16_f32 v181, v96, v97
	v_cvt_pk_bf16_f32 v90, v172, v175
	v_cvt_pk_bf16_f32 v91, v173, v176
	v_cvt_pk_bf16_f32 v92, v174, v177
	v_mfma_f32_32x32x16_bf16 v[98:113], v[218:221], v[222:225], v[98:113]
	v_cvt_pk_bf16_f32 v93, v170, v171
	v_cvt_pk_bf16_f32 v94, v166, v168
	v_cvt_pk_bf16_f32 v95, v167, v169
	v_cvt_pk_bf16_f32 v96, v162, v164
	v_cvt_pk_bf16_f32 v97, v163, v165
	v_cvt_pk_bf16_f32 v174, v82, v83
	v_cvt_pk_bf16_f32 v175, v84, v85
	v_mfma_f32_32x32x16_bf16 v[114:129], v[210:213], v[226:229], v[114:129]
	v_cvt_pk_bf16_f32 v176, v86, v87
	v_cvt_pk_bf16_f32 v177, v88, v89
	v_mov_b32_e32 v210, v251
	v_mov_b32_e32 v211, v251
	s_nop 1
	v_permlane32_swap_b32_e32 v210, v211
	v_permlane32_swap_b32_e32 v90, v92
	v_mfma_f32_32x32x16_bf16 v[98:113], v[214:217], v[226:229], v[98:113]
	v_permlane32_swap_b32_e32 v91, v93
	v_permlane32_swap_b32_e32 v94, v96
	v_permlane32_swap_b32_e32 v95, v97
	v_permlane32_swap_b32_e32 v174, v176
	v_permlane32_swap_b32_e32 v175, v177
	v_permlane32_swap_b32_e32 v178, v180
	v_permlane32_swap_b32_e32 v179, v181
	s_sub_i32 s0, s76, 64
	s_ashr_i32 s1, s0, 31
	s_lshl_b64 s[84:85], s[0:1], 10
	v_lshl_add_u64 v[82:83], v[192:193], 0, s[84:85]
	s_add_i32 s84, s76, 0xffffff80
	s_ashr_i32 s85, s84, 31
	s_lshl_b64 vcc, s[0:1], 7
	s_lshl_b64 s[84:85], s[84:85], 10
	s_add_u32 s84, s33, s84
	s_addc_u32 s85, s82, s85
	global_load_dwordx4 v[162:165], v[82:83], off
	global_load_dwordx4 v[166:169], v[82:83], off offset:128
	v_lshl_add_u64 v[82:83], v[190:191], 0, vcc
	v_lshl_add_u64 v[86:87], v[0:1], 1, s[84:85]
	global_load_dwordx4 v[170:173], v[82:83], off
	s_nop 0
	global_load_dwordx4 v[82:85], v[86:87], off
	v_add_co_u32_e32 v86, vcc, s81, v86
	s_nop 1
	v_addc_co_u32_e32 v87, vcc, 0, v87, vcc
	global_load_dwordx4 v[86:89], v[86:87], off
	ds_read_b64_tr_b16 v[212:213], v202 offset:0
	ds_read_b64_tr_b16 v[214:215], v202 offset:0x800
	ds_read_b64_tr_b16 v[216:217], v202 offset:0x1000
	ds_read_b64_tr_b16 v[218:219], v202 offset:0x1800
	ds_read_b64_tr_b16 v[220:221], v202 offset:0x2000
	ds_read_b64_tr_b16 v[222:223], v202 offset:0x2800
	ds_read_b64_tr_b16 v[224:225], v202 offset:0x3000
	ds_read_b64_tr_b16 v[226:227], v202 offset:0x3800
	ds_read_b64_tr_b16 v[228:229], v202 offset:0x200
	ds_read_b64_tr_b16 v[230:231], v202 offset:0xa00
	ds_read_b64_tr_b16 v[232:233], v202 offset:0x1200
	ds_read_b64_tr_b16 v[234:235], v202 offset:0x1a00
	ds_read_b64_tr_b16 v[236:237], v202 offset:0x2200
	ds_read_b64_tr_b16 v[238:239], v202 offset:0x2a00
	ds_read_b64_tr_b16 v[240:241], v202 offset:0x3200
	ds_read_b64_tr_b16 v[242:243], v202 offset:0x3a00
	s_nop 0
	s_waitcnt lgkmcnt(8)
	s_nop 0
	v_mfma_f32_32x32x16_bf16 v[18:33], v[90:93], v[212:215], v[18:33]
	ds_read_b64_tr_b16 v[212:213], v202 offset:0x400
	ds_read_b64_tr_b16 v[214:215], v202 offset:0xc00
	v_mfma_f32_32x32x16_bf16 v[18:33], v[94:97], v[216:219], v[18:33]
	ds_read_b64_tr_b16 v[216:217], v202 offset:0x1400
	ds_read_b64_tr_b16 v[218:219], v202 offset:0x1c00
	v_mfma_f32_32x32x16_bf16 v[18:33], v[174:177], v[220:223], v[18:33]
	ds_read_b64_tr_b16 v[220:221], v202 offset:0x2400
	ds_read_b64_tr_b16 v[222:223], v202 offset:0x2c00
	v_mfma_f32_32x32x16_bf16 v[18:33], v[178:181], v[224:227], v[18:33]
	ds_read_b64_tr_b16 v[224:225], v202 offset:0x3400
	ds_read_b64_tr_b16 v[226:227], v202 offset:0x3c00
	s_waitcnt lgkmcnt(8)
	s_nop 0
	v_mfma_f32_32x32x16_bf16 v[50:65], v[90:93], v[228:231], v[50:65]
	ds_read_b64_tr_b16 v[228:229], v202 offset:0x600
	ds_read_b64_tr_b16 v[230:231], v202 offset:0xe00
	v_mfma_f32_32x32x16_bf16 v[50:65], v[94:97], v[232:235], v[50:65]
	ds_read_b64_tr_b16 v[232:233], v202 offset:0x1600
	ds_read_b64_tr_b16 v[234:235], v202 offset:0x1e00
	v_mfma_f32_32x32x16_bf16 v[50:65], v[174:177], v[236:239], v[50:65]
	ds_read_b64_tr_b16 v[236:237], v202 offset:0x2600
	ds_read_b64_tr_b16 v[238:239], v202 offset:0x2e00
	v_mfma_f32_32x32x16_bf16 v[50:65], v[178:181], v[240:243], v[50:65]
	ds_read_b64_tr_b16 v[240:241], v202 offset:0x3600
	ds_read_b64_tr_b16 v[242:243], v202 offset:0x3e00
	s_waitcnt lgkmcnt(8)
	s_nop 0
	s_waitcnt lgkmcnt(0)
	v_mfma_f32_32x32x16_bf16 v[34:49], v[90:93], v[212:215], v[34:49]
	v_mfma_f32_32x32x16_bf16 v[2:17], v[90:93], v[228:231], v[2:17]
	v_max_f32_e32 v90, v115, v115
	v_max_f32_e32 v91, v114, v114
	v_max_f32_e32 v90, v91, v90
	v_max3_f32 v90, v90, v116, v117
	v_max3_f32 v90, v90, v118, v119
	v_max3_f32 v90, v90, v120, v121
	v_max3_f32 v90, v90, v122, v123
	v_mfma_f32_32x32x16_bf16 v[34:49], v[94:97], v[216:219], v[34:49]
	v_max3_f32 v90, v90, v124, v125
	v_max3_f32 v90, v90, v126, v127
	v_max3_f32 v90, v90, v128, v129
	v_max3_f32 v90, v90, v98, v99
	v_max3_f32 v90, v90, v100, v101
	v_max3_f32 v90, v90, v102, v103
	v_max3_f32 v90, v90, v104, v105
	v_mfma_f32_32x32x16_bf16 v[2:17], v[94:97], v[232:235], v[2:17]
	v_max3_f32 v90, v90, v106, v107
	v_max3_f32 v90, v90, v108, v109
	v_max3_f32 v90, v90, v110, v111
	v_max3_f32 v90, v90, v112, v113
	v_mov_b32_e32 v91, v90
	s_nop 1
	v_permlane32_swap_b32_e32 v90, v91
	v_mfma_f32_32x32x16_bf16 v[34:49], v[174:177], v[220:223], v[34:49]
	v_max_f32_e32 v91, v91, v91
	v_max_f32_e32 v90, v90, v90
	v_max_f32_e32 v90, v90, v91
	v_cmp_lt_f32_e32 vcc, s89, v90
	v_mfma_f32_32x32x16_bf16 v[2:17], v[174:177], v[236:239], v[2:17]
	v_mfma_f32_32x32x16_bf16 v[34:49], v[178:181], v[224:227], v[34:49]
	v_mfma_f32_32x32x16_bf16 v[2:17], v[178:181], v[240:243], v[2:17]
	s_cbranch_vccnz .LBB0_576
	v_mov_b32_e32 v212, 1.0
	v_cmp_gt_f32_e32 vcc, 1.0, v212
	s_cbranch_vccz .LBB0_563

; #define SBAR() __builtin_amdgcn_sched_barrier(0)
; #define LGKM_W2(n, x, y) asm volatile("s_waitcnt lgkmcnt(" #n ")" : "+v"(x), "+v"(y) :: "memory")
; __device__ __forceinline__ void qkt(f32x16& p0, f32x16& p1, const char* Kn, const char* Kr, const char* Qr, const bf16x8* qr, const f32x16& negm, int lane) {
;   const int kn = (int)(uintptr_t)Kn + (lane & 31) * 16 + (lane >> 5) * 1024, kr = (int)(uintptr_t)Kr + (lane & 31) * 16 + (lane >> 5) * 1024, qa = (int)(uintptr_t)Qr + lane * 16;
;   bf16x8 a0, a1, b0, b1, qa_, qb_;
;     ...
;   a0 = dsr128<0 * 2048>(kn); a1 = dsr128<0 * 2048 + 512>(kn);
;   b0 = dsr128<1 * 2048>(kn); b1 = dsr128<1 * 2048 + 512>(kn); LGKM_W2(2, a0, a1);
;   p0 = __builtin_amdgcn_mfma_f32_32x32x16_bf16(a0, qr[0], negm, 0, 0, 0); p1 = __builtin_amdgcn_mfma_f32_32x32x16_bf16(a1, qr[0], negm, 0, 0, 0);
;   a0 = dsr128<2 * 2048>(kn); a1 = dsr128<2 * 2048 + 512>(kn); LGKM_W2(2, b0, b1); MM(b0, b1, qr[1]);
;   b0 = dsr128<3 * 2048>(kn); b1 = dsr128<3 * 2048 + 512>(kn); LGKM_W2(2, a0, a1); MM(a0, a1, qr[2]);
;   a0 = dsr128<4 * 2048>(kn); a1 = dsr128<4 * 2048 + 512>(kn); LGKM_W2(2, b0, b1); MM(b0, b1, qr[3]);
;   b0 = dsr128<5 * 2048>(kn); b1 = dsr128<5 * 2048 + 512>(kn); LGKM_W2(2, a0, a1); MM(a0, a1, qr[4]);
;   a0 = dsr128<6 * 2048>(kn); a1 = dsr128<6 * 2048 + 512>(kn); LGKM_W2(2, b0, b1); MM(b0, b1, qr[5]);
;   b0 = dsr128<7 * 2048>(kn); b1 = dsr128<7 * 2048 + 512>(kn); LGKM_W2(2, a0, a1); MM(a0, a1, qr[6]);
;   a0 = dsr128<0 * 2048>(kr); a1 = dsr128<0 * 2048 + 512>(kr); qa_ = dsr128<0 * 1024>(qa); LGKM_W2(3, b0, b1); MM(b0, b1, qr[7]);
;   b0 = dsr128<1 * 2048>(kr); b1 = dsr128<1 * 2048 + 512>(kr); qb_ = dsr128<1 * 1024>(qa); LGKM_W3(3, a0, a1, qa_); MM(a0, a1, qa_);
;   a0 = dsr128<2 * 2048>(kr); a1 = dsr128<2 * 2048 + 512>(kr); qa_ = dsr128<2 * 1024>(qa); LGKM_W3(3, b0, b1, qb_); MM(b0, b1, qb_);
;   b0 = dsr128<3 * 2048>(kr); b1 = dsr128<3 * 2048 + 512>(kr); qb_ = dsr128<3 * 1024>(qa); LGKM_W3(3, a0, a1, qa_); MM(a0, a1, qa_);
;   LGKM_W3(0, b0, b1, qb_); MM(b0, b1, qb_);
; __device__ __forceinline__ void attn_unit(const bf16* __restrict__ Qg, const bf16* __restrict__ KNg, const bf16* __restrict__ KRg, const bf16* __restrict__ Vg, bf16* __restrict__ AO, ...
;     ...
;     SWAIT(); KWRITE(0); VWRITE(1); __syncthreads();
;     SBAR(); qkt(pA0, pA1, KN_lds, KR_lds, QR_lds, qr, negm, lane);
;     finishSM(pB0, pB1, alB, l_reg, pa0, pa1, pa2, pa3); SBAR();
.LBB0_563:
	s_lshl_b64 vcc, s[0:1], 9
	v_exp_f32_e32 v230, v114
	v_exp_f32_e32 v231, v115
	v_exp_f32_e32 v232, v116
	v_exp_f32_e32 v233, v117
	v_exp_f32_e32 v234, v118
	v_exp_f32_e32 v235, v119
	s_waitcnt vmcnt(0)
	ds_write_b128 v197, v[162:165] offset:32768
	ds_write_b128 v197, v[166:169] offset:40960
	ds_write_b128 v200, v[170:173]
	ds_write_b128 v198, v[82:85] offset:16384
	ds_write_b128 v199, v[86:89] offset:16384
	v_exp_f32_e32 v236, v120
	v_exp_f32_e32 v237, v121
	v_exp_f32_e32 v238, v122
	v_exp_f32_e32 v239, v123
	v_exp_f32_e32 v240, v124
	v_exp_f32_e32 v241, v125
	v_exp_f32_e32 v242, v126
	v_exp_f32_e32 v243, v127
	v_exp_f32_e32 v244, v128
	v_exp_f32_e32 v245, v129
	s_waitcnt lgkmcnt(0)
	s_barrier
	ds_read_b128 v[82:85], v187 offset:0
	ds_read_b128 v[174:177], v187 offset:0x200
	ds_read_b128 v[178:181], v187 offset:0x800
	ds_read_b128 v[214:217], v187 offset:0xa00
	v_exp_f32_e32 v98, v98
	s_waitcnt lgkmcnt(2)
	v_exp_f32_e32 v99, v99
	v_mfma_f32_32x32x16_bf16 v[114:129], v[82:85], v[130:133], v[66:81]
	v_exp_f32_e32 v100, v100
	v_exp_f32_e32 v101, v101
	v_exp_f32_e32 v102, v102
	v_exp_f32_e32 v103, v103
	v_exp_f32_e32 v104, v104
	v_exp_f32_e32 v105, v105
	v_mfma_f32_32x32x16_bf16 v[82:97], v[174:177], v[130:133], v[66:81]
	v_exp_f32_e32 v106, v106
	v_add_f32_e32 v251, 0, v230
	v_add_f32_e32 v251, v231, v251
	ds_read_b128 v[174:177], v187 offset:0x1000
	ds_read_b128 v[218:221], v187 offset:0x1200
	s_waitcnt lgkmcnt(2)
	s_nop 0
	v_mfma_f32_32x32x16_bf16 v[114:129], v[178:181], v[134:137], v[114:129]
	v_add_f32_e32 v251, v232, v251
	v_exp_f32_e32 v107, v107
	v_add_f32_e32 v251, v233, v251
	ds_read_b128 v[178:181], v187 offset:0x1800
	v_mfma_f32_32x32x16_bf16 v[82:97], v[214:217], v[134:137], v[82:97]
	v_add_f32_e32 v251, v234, v251
	v_add_f32_e32 v251, v235, v251
	v_exp_f32_e32 v108, v108
	ds_read_b128 v[214:217], v187 offset:0x1a00
	s_waitcnt lgkmcnt(2)
	s_nop 0
	v_mfma_f32_32x32x16_bf16 v[114:129], v[174:177], v[138:141], v[114:129]
	v_add_f32_e32 v251, v236, v251
	v_add_f32_e32 v251, v237, v251
	v_add_f32_e32 v251, v238, v251
	ds_read_b128 v[174:177], v187 offset:0x2000
	v_mfma_f32_32x32x16_bf16 v[82:97], v[218:221], v[138:141], v[82:97]
	v_exp_f32_e32 v109, v109
	v_add_f32_e32 v251, v239, v251
	v_add_f32_e32 v251, v240, v251
	ds_read_b128 v[218:221], v187 offset:0x2200
	s_waitcnt lgkmcnt(2)
	s_nop 0
	v_mfma_f32_32x32x16_bf16 v[114:129], v[178:181], v[142:145], v[114:129]
	v_add_f32_e32 v251, v241, v251
	v_exp_f32_e32 v110, v110
	v_add_f32_e32 v251, v242, v251
	ds_read_b128 v[178:181], v187 offset:0x2800
	v_mfma_f32_32x32x16_bf16 v[82:97], v[214:217], v[142:145], v[82:97]
	v_add_f32_e32 v251, v243, v251
	v_add_f32_e32 v251, v244, v251
	v_exp_f32_e32 v111, v111
	ds_read_b128 v[214:217], v187 offset:0x2a00
	s_waitcnt lgkmcnt(2)
	s_nop 0
	v_mfma_f32_32x32x16_bf16 v[114:129], v[174:177], v[146:149], v[114:129]
	v_add_f32_e32 v251, v245, v251
	v_add_f32_e32 v251, v98, v251
	v_add_f32_e32 v251, v99, v251
	ds_read_b128 v[174:177], v187 offset:0x3000
	v_mfma_f32_32x32x16_bf16 v[82:97], v[218:221], v[146:149], v[82:97]
	v_exp_f32_e32 v112, v112
	v_add_f32_e32 v251, v100, v251
	v_add_f32_e32 v251, v101, v251
	ds_read_b128 v[218:221], v187 offset:0x3200
	s_waitcnt lgkmcnt(2)
	s_nop 0
	v_mfma_f32_32x32x16_bf16 v[114:129], v[178:181], v[150:153], v[114:129]
	v_add_f32_e32 v251, v102, v251
	v_exp_f32_e32 v113, v113
	v_add_f32_e32 v251, v103, v251
	ds_read_b128 v[178:181], v187 offset:0x3800
	v_mfma_f32_32x32x16_bf16 v[82:97], v[214:217], v[150:153], v[82:97]
	v_add_f32_e32 v251, v104, v251
	v_add_f32_e32 v251, v105, v251
	v_add_f32_e32 v251, v106, v251
	v_add_f32_e32 v251, v107, v251
	ds_read_b128 v[214:217], v187 offset:0x3a00
	s_waitcnt lgkmcnt(2)
	s_nop 0
	v_mfma_f32_32x32x16_bf16 v[114:129], v[174:177], v[154:157], v[114:129]
	v_add_f32_e32 v251, v108, v251
	v_add_f32_e32 v251, v109, v251
	v_add_f32_e32 v251, v110, v251
	v_add_f32_e32 v251, v111, v251
	ds_read_b128 v[174:177], v203 offset:0
	v_mfma_f32_32x32x16_bf16 v[82:97], v[218:221], v[154:157], v[82:97]
	v_add_f32_e32 v251, v112, v251
	v_add_f32_e32 v251, v113, v251
	ds_read_b128 v[218:221], v203 offset:0x200
	ds_read_b128 v[222:225], v189 offset:0
	s_waitcnt lgkmcnt(3)
	s_nop 0
	v_mfma_f32_32x32x16_bf16 v[114:129], v[178:181], v[158:161], v[114:129]
	ds_read_b128 v[178:181], v203 offset:0x800
	v_mfma_f32_32x32x16_bf16 v[82:97], v[214:217], v[158:161], v[82:97]
	ds_read_b128 v[214:217], v203 offset:0xa00
	ds_read_b128 v[226:229], v189 offset:0x400
	s_waitcnt lgkmcnt(3)
	s_nop 0
	v_mfma_f32_32x32x16_bf16 v[114:129], v[174:177], v[222:225], v[114:129]
	ds_read_b128 v[174:177], v203 offset:0x1000
	v_mfma_f32_32x32x16_bf16 v[82:97], v[218:221], v[222:225], v[82:97]
	ds_read_b128 v[218:221], v203 offset:0x1200
	ds_read_b128 v[222:225], v189 offset:0x800
	s_waitcnt lgkmcnt(3)
	s_nop 0
	v_mfma_f32_32x32x16_bf16 v[114:129], v[178:181], v[226:229], v[114:129]
	ds_read_b128 v[178:181], v203 offset:0x1800
	v_mfma_f32_32x32x16_bf16 v[82:97], v[214:217], v[226:229], v[82:97]
	ds_read_b128 v[214:217], v203 offset:0x1a00
	ds_read_b128 v[226:229], v189 offset:0xc00
	s_waitcnt lgkmcnt(3)
	s_nop 0
	s_waitcnt lgkmcnt(0)
	v_mfma_f32_32x32x16_bf16 v[114:129], v[174:177], v[222:225], v[114:129]
	v_mfma_f32_32x32x16_bf16 v[114:129], v[178:181], v[226:229], v[114:129]
	v_cvt_pk_bf16_f32 v178, v106, v107
	v_cvt_pk_bf16_f32 v179, v108, v109
	v_cvt_pk_bf16_f32 v180, v110, v111
	v_cvt_pk_bf16_f32 v181, v112, v113
	v_cvt_pk_bf16_f32 v106, v230, v231
	v_cvt_pk_bf16_f32 v107, v232, v233
	v_cvt_pk_bf16_f32 v108, v234, v235
	v_mfma_f32_32x32x16_bf16 v[82:97], v[218:221], v[222:225], v[82:97]
	v_cvt_pk_bf16_f32 v109, v236, v237
	v_cvt_pk_bf16_f32 v110, v238, v239
	v_cvt_pk_bf16_f32 v111, v240, v241
	v_cvt_pk_bf16_f32 v112, v242, v243
	v_cvt_pk_bf16_f32 v113, v244, v245
	v_cvt_pk_bf16_f32 v174, v98, v99
	v_cvt_pk_bf16_f32 v175, v100, v101
	v_mfma_f32_32x32x16_bf16 v[82:97], v[214:217], v[226:229], v[82:97]
	v_cvt_pk_bf16_f32 v176, v102, v103
	v_cvt_pk_bf16_f32 v177, v104, v105
	v_mov_b32_e32 v213, v251
	v_mov_b32_e32 v214, v251
	s_nop 1
	v_permlane32_swap_b32_e32 v213, v214
	v_permlane32_swap_b32_e32 v106, v108
	v_permlane32_swap_b32_e32 v107, v109
	v_permlane32_swap_b32_e32 v110, v112
	v_permlane32_swap_b32_e32 v111, v113
	v_permlane32_swap_b32_e32 v174, v176
	v_permlane32_swap_b32_e32 v175, v177
	v_permlane32_swap_b32_e32 v178, v180
	v_permlane32_swap_b32_e32 v179, v181
	s_cmp_lt_u32 s83, s94
	s_cselect_b64 s[0:1], -1, 0
	s_cmp_ge_u32 s83, s94
	s_cbranch_scc1 .LBB0_565
	s_ashr_i32 s77, s76, 31
	s_lshl_b64 s[84:85], s[76:77], 10
	s_lshl_b64 s[86:87], s[76:77], 7
	v_lshl_add_u64 v[98:99], v[192:193], 0, s[84:85]
	global_load_dwordx4 v[162:165], v[98:99], off
	global_load_dwordx4 v[166:169], v[98:99], off offset:128
	v_lshl_add_u64 v[98:99], v[190:191], 0, s[86:87]
	global_load_dwordx4 v[170:173], v[98:99], off

; #define KWRITE(b) do { *(bf16x8*)(KN_lds + (b) * SHM_KN + kwoff) = ks0; *(bf16x8*)(KN_lds + (b) * SHM_KN + 8192 + kwoff) = ks1; *(bf16x8*)(KR_lds + (b) * SHM_KR + kwoff) = kr0; } while (0)
; #define VWRITE(b) do { *(bf16x8*)(V_lds + (b) * SHM_V + vst0) = vs0; *(bf16x8*)(V_lds + (b) * SHM_V + vst1) = vs1; } while (0)
; #define SWAIT() asm volatile("s_waitcnt vmcnt(0)" ::: "memory")
; #define RESC(a) do { if (__any((a) < 1.f)) { if (hi == 0) al_l[r32] = (a); asm volatile("s_waitcnt lgkmcnt(0)" ::: "memory"); \
;     _Pragma("unroll") for (int d = 0; d < 4; ++d) _Pragma("unroll") for (int r = 0; r < 16; ++r) o[d][r] *= al_l[crow(r, hi)]; } } while (0)
; template <bool START>
; __device__ __forceinline__ void partialSM(f32x16& p0, f32x16& p1, float& mhat, f32x16& negm, float& alpha) {
;     ...
;   for (int r = 0; r < 16; ++r) p0[r] = __builtin_amdgcn_exp2f(p0[r]);
; }
; __device__ __forceinline__ void finishSM(f32x16& p0, f32x16& p1, float alpha, float& l_reg, bf16x8& pa0, bf16x8& pa1, bf16x8& pa2, bf16x8& pa3) {
; #pragma unroll
;   for (int r = 0; r < 16; ++r) p1[r] = __builtin_amdgcn_exp2f(p1[r]);
;   float ps = 0;
; #pragma unroll
;   for (int r = 0; r < 16; ++r) ps += p0[r];
; #pragma unroll
;   for (int r = 0; r < 16; ++r) ps += p1[r];
;   { auto rr = __builtin_amdgcn_permlane32_swap(__float_as_uint(ps), __float_as_uint(ps), false, false);
;     ps = __uint_as_float(rr[0]) + __uint_as_float(rr[1]); }
;   l_reg = l_reg * alpha + ps;
; __device__ __forceinline__ void attn_unit(const bf16* __restrict__ Qg, const bf16* __restrict__ KNg, const bf16* __restrict__ KRg, const bf16* __restrict__ Vg, bf16* __restrict__ AO, ...
;     ...
;     partialSM<false>(pA0, pA1, mhat, negm, alA);
;     RESC(alA);
;     SWAIT(); if (more) KWRITE(1); VWRITE(0); __syncthreads();
.LBB0_574:
	s_waitcnt vmcnt(0)
	ds_write_b128 v198, v[98:101]
	ds_write_b128 v199, v[102:105]
	v_exp_f32_e32 v172, v114
	v_exp_f32_e32 v175, v115
	v_exp_f32_e32 v173, v116
	v_exp_f32_e32 v176, v117
	v_exp_f32_e32 v174, v118
	v_exp_f32_e32 v177, v119
	v_exp_f32_e32 v170, v120
	v_exp_f32_e32 v171, v121
	v_exp_f32_e32 v166, v122
	v_exp_f32_e32 v168, v123
	v_exp_f32_e32 v167, v124
	v_exp_f32_e32 v169, v125
	v_exp_f32_e32 v162, v126
	v_exp_f32_e32 v164, v127
	v_exp_f32_e32 v163, v128
	v_exp_f32_e32 v165, v129
	v_add_f32_e32 v107, v210, v211
	v_fmac_f32_e32 v107, v209, v208
	v_add_f32_e32 v208, v213, v214
	s_add_i32 s0, s83, 2
	s_addk_i32 s76, 0x80
	v_fmac_f32_e32 v208, v107, v212
	s_cmp_ge_u32 s83, s74
	s_waitcnt lgkmcnt(0)
	s_barrier
	s_cbranch_scc1 .LBB0_578
	s_mov_b32 s83, s0
	v_mov_b32_e32 v209, v106
	s_branch .LBB0_558

; #define SBAR() __builtin_amdgcn_sched_barrier(0)
; #define LGKM_W2(n, x, y) asm volatile("s_waitcnt lgkmcnt(" #n ")" : "+v"(x), "+v"(y) :: "memory")
; __device__ __forceinline__ void qkt(f32x16& p0, f32x16& p1, const char* Kn, const char* Kr, const char* Qr, const bf16x8* qr, const f32x16& negm, int lane) {
;   const int kn = (int)(uintptr_t)Kn + (lane & 31) * 16 + (lane >> 5) * 1024, kr = (int)(uintptr_t)Kr + (lane & 31) * 16 + (lane >> 5) * 1024, qa = (int)(uintptr_t)Qr + lane * 16;
;   bf16x8 a0, a1, b0, b1, qa_, qb_;
;     ...
;   a0 = dsr128<0 * 2048>(kn); a1 = dsr128<0 * 2048 + 512>(kn);
;   b0 = dsr128<1 * 2048>(kn); b1 = dsr128<1 * 2048 + 512>(kn); LGKM_W2(2, a0, a1);
;   p0 = __builtin_amdgcn_mfma_f32_32x32x16_bf16(a0, qr[0], negm, 0, 0, 0); p1 = __builtin_amdgcn_mfma_f32_32x32x16_bf16(a1, qr[0], negm, 0, 0, 0);
;   a0 = dsr128<2 * 2048>(kn); a1 = dsr128<2 * 2048 + 512>(kn); LGKM_W2(2, b0, b1); MM(b0, b1, qr[1]);
;   b0 = dsr128<3 * 2048>(kn); b1 = dsr128<3 * 2048 + 512>(kn); LGKM_W2(2, a0, a1); MM(a0, a1, qr[2]);
;   a0 = dsr128<4 * 2048>(kn); a1 = dsr128<4 * 2048 + 512>(kn); LGKM_W2(2, b0, b1); MM(b0, b1, qr[3]);
;   b0 = dsr128<5 * 2048>(kn); b1 = dsr128<5 * 2048 + 512>(kn); LGKM_W2(2, a0, a1); MM(a0, a1, qr[4]);
;   a0 = dsr128<6 * 2048>(kn); a1 = dsr128<6 * 2048 + 512>(kn); LGKM_W2(2, b0, b1); MM(b0, b1, qr[5]);
;   b0 = dsr128<7 * 2048>(kn); b1 = dsr128<7 * 2048 + 512>(kn); LGKM_W2(2, a0, a1); MM(a0, a1, qr[6]);
;   a0 = dsr128<0 * 2048>(kr); a1 = dsr128<0 * 2048 + 512>(kr); qa_ = dsr128<0 * 1024>(qa); LGKM_W2(3, b0, b1); MM(b0, b1, qr[7]);
;   b0 = dsr128<1 * 2048>(kr); b1 = dsr128<1 * 2048 + 512>(kr); qb_ = dsr128<1 * 1024>(qa); LGKM_W3(3, a0, a1, qa_); MM(a0, a1, qa_);
;   a0 = dsr128<2 * 2048>(kr); a1 = dsr128<2 * 2048 + 512>(kr); qa_ = dsr128<2 * 1024>(qa); LGKM_W3(3, b0, b1, qb_); MM(b0, b1, qb_);
;   b0 = dsr128<3 * 2048>(kr); b1 = dsr128<3 * 2048 + 512>(kr); qb_ = dsr128<3 * 1024>(qa); LGKM_W3(3, a0, a1, qa_); MM(a0, a1, qa_);
;   LGKM_W3(0, b0, b1, qb_); MM(b0, b1, qb_);
; __device__ __forceinline__ void attn_unit(const bf16* __restrict__ Qg, const bf16* __restrict__ KNg, const bf16* __restrict__ KRg, const bf16* __restrict__ Vg, bf16* __restrict__ AO, ...
;     ...
;     SWAIT(); KWRITE(0); VWRITE(1); __syncthreads();
;     SBAR(); qkt(pA0, pA1, KN_lds, KR_lds, QR_lds, qr, negm, lane);
;     finishSM(pB0, pB1, alB, l_reg, pa0, pa1, pa2, pa3); SBAR();
.LBB0_1377:
	v_exp_f32_e32 v234, v114
	v_exp_f32_e32 v235, v115
	v_exp_f32_e32 v236, v116
	v_exp_f32_e32 v237, v117
	v_exp_f32_e32 v238, v118
	v_exp_f32_e32 v239, v119
	s_waitcnt vmcnt(0)
	ds_write_b128 v202, v[162:165] offset:32768
	ds_write_b128 v202, v[166:169] offset:40960
	ds_write_b128 v205, v[170:173]
	ds_write_b128 v203, v[82:85] offset:16384
	ds_write_b128 v204, v[86:89] offset:16384
	v_exp_f32_e32 v240, v120
	v_exp_f32_e32 v241, v121
	v_exp_f32_e32 v242, v122
	v_exp_f32_e32 v243, v123
	v_exp_f32_e32 v244, v124
	v_exp_f32_e32 v245, v125
	v_exp_f32_e32 v246, v126
	v_exp_f32_e32 v247, v127
	v_exp_f32_e32 v248, v128
	v_exp_f32_e32 v249, v129
	s_waitcnt lgkmcnt(0)
	s_barrier
	ds_read_b128 v[82:85], v208 offset:0
	ds_read_b128 v[174:177], v208 offset:0x200
	ds_read_b128 v[178:181], v208 offset:0x800
	ds_read_b128 v[218:221], v208 offset:0xa00
	v_exp_f32_e32 v98, v98
	s_waitcnt lgkmcnt(2)
	v_exp_f32_e32 v99, v99
	v_mfma_f32_32x32x16_bf16 v[114:129], v[82:85], v[130:133], v[66:81]
	v_exp_f32_e32 v100, v100
	v_exp_f32_e32 v101, v101
	v_exp_f32_e32 v102, v102
	v_exp_f32_e32 v103, v103
	v_exp_f32_e32 v104, v104
	v_exp_f32_e32 v105, v105
	v_mfma_f32_32x32x16_bf16 v[82:97], v[174:177], v[130:133], v[66:81]
	v_exp_f32_e32 v106, v106
	v_add_f32_e32 v251, 0, v234
	v_add_f32_e32 v251, v235, v251
	ds_read_b128 v[174:177], v208 offset:0x1000
	ds_read_b128 v[222:225], v208 offset:0x1200
	s_waitcnt lgkmcnt(2)
	s_nop 0
	v_mfma_f32_32x32x16_bf16 v[114:129], v[178:181], v[134:137], v[114:129]
	v_add_f32_e32 v251, v236, v251
	v_exp_f32_e32 v107, v107
	v_add_f32_e32 v251, v237, v251
	ds_read_b128 v[178:181], v208 offset:0x1800
	v_mfma_f32_32x32x16_bf16 v[82:97], v[218:221], v[134:137], v[82:97]
	v_add_f32_e32 v251, v238, v251
	v_add_f32_e32 v251, v239, v251
	v_exp_f32_e32 v108, v108
	ds_read_b128 v[218:221], v208 offset:0x1a00
	s_waitcnt lgkmcnt(2)
	s_nop 0
	v_mfma_f32_32x32x16_bf16 v[114:129], v[174:177], v[138:141], v[114:129]
	v_add_f32_e32 v251, v240, v251
	v_add_f32_e32 v251, v241, v251
	v_add_f32_e32 v251, v242, v251
	ds_read_b128 v[174:177], v208 offset:0x2000
	v_mfma_f32_32x32x16_bf16 v[82:97], v[222:225], v[138:141], v[82:97]
	v_exp_f32_e32 v109, v109
	v_add_f32_e32 v251, v243, v251
	v_add_f32_e32 v251, v244, v251
	ds_read_b128 v[222:225], v208 offset:0x2200
	s_waitcnt lgkmcnt(2)
	s_nop 0
	v_mfma_f32_32x32x16_bf16 v[114:129], v[178:181], v[142:145], v[114:129]
	v_add_f32_e32 v251, v245, v251
	v_exp_f32_e32 v110, v110
	v_add_f32_e32 v251, v246, v251
	ds_read_b128 v[178:181], v208 offset:0x2800
	v_mfma_f32_32x32x16_bf16 v[82:97], v[218:221], v[142:145], v[82:97]
	v_add_f32_e32 v251, v247, v251
	v_add_f32_e32 v251, v248, v251
	v_exp_f32_e32 v111, v111
	ds_read_b128 v[218:221], v208 offset:0x2a00
	s_waitcnt lgkmcnt(2)
	s_nop 0
	v_mfma_f32_32x32x16_bf16 v[114:129], v[174:177], v[146:149], v[114:129]
	v_add_f32_e32 v251, v249, v251
	v_add_f32_e32 v251, v98, v251
	v_add_f32_e32 v251, v99, v251
	ds_read_b128 v[174:177], v208 offset:0x3000
	v_mfma_f32_32x32x16_bf16 v[82:97], v[222:225], v[146:149], v[82:97]
	v_exp_f32_e32 v112, v112
	v_add_f32_e32 v251, v100, v251
	v_add_f32_e32 v251, v101, v251
	ds_read_b128 v[222:225], v208 offset:0x3200
	s_waitcnt lgkmcnt(2)
	s_nop 0
	v_mfma_f32_32x32x16_bf16 v[114:129], v[178:181], v[150:153], v[114:129]
	v_add_f32_e32 v251, v102, v251
	v_exp_f32_e32 v113, v113
	v_add_f32_e32 v251, v103, v251
	ds_read_b128 v[178:181], v208 offset:0x3800
	v_mfma_f32_32x32x16_bf16 v[82:97], v[218:221], v[150:153], v[82:97]
	v_add_f32_e32 v251, v104, v251
	v_add_f32_e32 v251, v105, v251
	v_add_f32_e32 v251, v106, v251
	v_add_f32_e32 v251, v107, v251
	ds_read_b128 v[218:221], v208 offset:0x3a00
	s_waitcnt lgkmcnt(2)
	s_nop 0
	v_mfma_f32_32x32x16_bf16 v[114:129], v[174:177], v[154:157], v[114:129]
	v_add_f32_e32 v251, v108, v251
	v_add_f32_e32 v251, v109, v251
	v_add_f32_e32 v251, v110, v251
	v_add_f32_e32 v251, v111, v251
	ds_read_b128 v[174:177], v209 offset:0
	v_mfma_f32_32x32x16_bf16 v[82:97], v[222:225], v[154:157], v[82:97]
	v_add_f32_e32 v251, v112, v251
	v_add_f32_e32 v251, v113, v251
	ds_read_b128 v[222:225], v209 offset:0x200
	ds_read_b128 v[226:229], v201 offset:0
	s_waitcnt lgkmcnt(3)
	s_nop 0
	v_mfma_f32_32x32x16_bf16 v[114:129], v[178:181], v[158:161], v[114:129]
	ds_read_b128 v[178:181], v209 offset:0x800
	v_mfma_f32_32x32x16_bf16 v[82:97], v[218:221], v[158:161], v[82:97]
	ds_read_b128 v[218:221], v209 offset:0xa00
	ds_read_b128 v[230:233], v201 offset:0x400
	s_waitcnt lgkmcnt(3)
	s_nop 0
	v_mfma_f32_32x32x16_bf16 v[114:129], v[174:177], v[226:229], v[114:129]
	ds_read_b128 v[174:177], v209 offset:0x1000
	v_mfma_f32_32x32x16_bf16 v[82:97], v[222:225], v[226:229], v[82:97]
	ds_read_b128 v[222:225], v209 offset:0x1200
	ds_read_b128 v[226:229], v201 offset:0x800
	s_waitcnt lgkmcnt(3)
	s_nop 0
	v_mfma_f32_32x32x16_bf16 v[114:129], v[178:181], v[230:233], v[114:129]
	ds_read_b128 v[178:181], v209 offset:0x1800
	v_mfma_f32_32x32x16_bf16 v[82:97], v[218:221], v[230:233], v[82:97]
	ds_read_b128 v[218:221], v209 offset:0x1a00
	ds_read_b128 v[230:233], v201 offset:0xc00
	s_waitcnt lgkmcnt(3)
	s_nop 0
	s_waitcnt lgkmcnt(0)
	v_mfma_f32_32x32x16_bf16 v[114:129], v[174:177], v[226:229], v[114:129]
	v_mfma_f32_32x32x16_bf16 v[114:129], v[178:181], v[230:233], v[114:129]
	v_cvt_pk_bf16_f32 v178, v106, v107
	v_cvt_pk_bf16_f32 v179, v108, v109
	v_cvt_pk_bf16_f32 v180, v110, v111
	v_cvt_pk_bf16_f32 v181, v112, v113
	v_cvt_pk_bf16_f32 v106, v234, v235
	v_cvt_pk_bf16_f32 v107, v236, v237
	v_cvt_pk_bf16_f32 v108, v238, v239
	v_mfma_f32_32x32x16_bf16 v[82:97], v[222:225], v[226:229], v[82:97]
	v_cvt_pk_bf16_f32 v109, v240, v241
	v_cvt_pk_bf16_f32 v110, v242, v243
	v_cvt_pk_bf16_f32 v111, v244, v245
	v_cvt_pk_bf16_f32 v112, v246, v247
	v_cvt_pk_bf16_f32 v113, v248, v249
	v_cvt_pk_bf16_f32 v174, v98, v99
	v_cvt_pk_bf16_f32 v175, v100, v101
	v_mfma_f32_32x32x16_bf16 v[82:97], v[218:221], v[230:233], v[82:97]
	v_cvt_pk_bf16_f32 v176, v102, v103
	v_cvt_pk_bf16_f32 v177, v104, v105
	v_mov_b32_e32 v218, v251
	v_mov_b32_e32 v219, v251
	s_nop 1
	v_permlane32_swap_b32_e32 v218, v219
	v_permlane32_swap_b32_e32 v106, v108
	v_permlane32_swap_b32_e32 v107, v109
	v_permlane32_swap_b32_e32 v110, v112
	v_permlane32_swap_b32_e32 v111, v113
	v_permlane32_swap_b32_e32 v174, v176
	v_permlane32_swap_b32_e32 v175, v177
	v_permlane32_swap_b32_e32 v178, v180
	v_permlane32_swap_b32_e32 v179, v181
	s_cmp_lt_u32 s91, s96
	s_cselect_b64 s[0:1], -1, 0
	s_cmp_ge_u32 s91, s96
	s_cbranch_scc1 .LBB0_1379
	v_add_co_u32_e32 v98, vcc, 0x60f0000, v196
	s_nop 1
	v_addc_co_u32_e32 v99, vcc, 0, v197, vcc
	global_load_dwordx4 v[162:165], v[98:99], off
	global_load_dwordx4 v[166:169], v[98:99], off offset:128
	v_add_co_u32_e32 v98, vcc, 0xe1c6000, v194
	s_nop 1
	v_addc_co_u32_e32 v99, vcc, 0, v195, vcc
	global_load_dwordx4 v[170:173], v[98:99], off

; #define KWRITE(b) do { *(bf16x8*)(KN_lds + (b) * SHM_KN + kwoff) = ks0; *(bf16x8*)(KN_lds + (b) * SHM_KN + 8192 + kwoff) = ks1; *(bf16x8*)(KR_lds + (b) * SHM_KR + kwoff) = kr0; } while (0)
; #define VWRITE(b) do { *(bf16x8*)(V_lds + (b) * SHM_V + vst0) = vs0; *(bf16x8*)(V_lds + (b) * SHM_V + vst1) = vs1; } while (0)
; #define SWAIT() asm volatile("s_waitcnt vmcnt(0)" ::: "memory")
; #define RESC(a) do { if (__any((a) < 1.f)) { if (hi == 0) al_l[r32] = (a); asm volatile("s_waitcnt lgkmcnt(0)" ::: "memory"); \
;     _Pragma("unroll") for (int d = 0; d < 4; ++d) _Pragma("unroll") for (int r = 0; r < 16; ++r) o[d][r] *= al_l[crow(r, hi)]; } } while (0)
; template <bool START>
; __device__ __forceinline__ void partialSM(f32x16& p0, f32x16& p1, float& mhat, f32x16& negm, float& alpha) {
;     ...
;   for (int r = 0; r < 16; ++r) p0[r] = __builtin_amdgcn_exp2f(p0[r]);
; }
; __device__ __forceinline__ void finishSM(f32x16& p0, f32x16& p1, float alpha, float& l_reg, bf16x8& pa0, bf16x8& pa1, bf16x8& pa2, bf16x8& pa3) {
; #pragma unroll
;   for (int r = 0; r < 16; ++r) p1[r] = __builtin_amdgcn_exp2f(p1[r]);
;   float ps = 0;
; #pragma unroll
;   for (int r = 0; r < 16; ++r) ps += p0[r];
; #pragma unroll
;   for (int r = 0; r < 16; ++r) ps += p1[r];
;   { auto rr = __builtin_amdgcn_permlane32_swap(__float_as_uint(ps), __float_as_uint(ps), false, false);
;     ps = __uint_as_float(rr[0]) + __uint_as_float(rr[1]); }
;   l_reg = l_reg * alpha + ps;
; __device__ __forceinline__ void attn_unit(const bf16* __restrict__ Qg, const bf16* __restrict__ KNg, const bf16* __restrict__ KRg, const bf16* __restrict__ Vg, bf16* __restrict__ AO, ...
;     ...
;     partialSM<false>(pA0, pA1, mhat, negm, alA);
;     RESC(alA);
;     SWAIT(); if (more) KWRITE(1); VWRITE(0); __syncthreads();
.LBB0_1388:
	s_waitcnt vmcnt(0)
	ds_write_b128 v203, v[98:101]
	ds_write_b128 v204, v[102:105]
	v_exp_f32_e32 v172, v114
	v_exp_f32_e32 v175, v115
	v_exp_f32_e32 v173, v116
	v_exp_f32_e32 v176, v117
	v_exp_f32_e32 v174, v118
	v_exp_f32_e32 v177, v119
	v_exp_f32_e32 v170, v120
	v_exp_f32_e32 v171, v121
	v_exp_f32_e32 v166, v122
	v_exp_f32_e32 v168, v123
	v_exp_f32_e32 v167, v124
	v_exp_f32_e32 v169, v125
	v_exp_f32_e32 v162, v126
	v_exp_f32_e32 v164, v127
	v_exp_f32_e32 v163, v128
	v_exp_f32_e32 v165, v129
	v_add_f32_e32 v0, v0, v216
	v_fmac_f32_e32 v0, v215, v214
	v_add_f32_e32 v214, v218, v219
	s_add_i32 s0, s91, 2
	v_fmac_f32_e32 v214, v0, v217
	v_lshl_add_u64 v[186:187], v[186:187], 0, s[80:81]
	v_lshl_add_u64 v[188:189], v[188:189], 0, s[82:83]
	s_cmp_ge_u32 s91, s90
	v_lshl_add_u64 v[190:191], v[190:191], 0, s[82:83]
	s_waitcnt lgkmcnt(0)
	s_barrier
	s_cbranch_scc1 .LBB0_1392
	s_mov_b32 s91, s0
	v_mov_b32_e32 v215, v106
	s_branch .LBB0_1372

; __global__ void __launch_bounds__(NWAVES * 64, 2) mega_fwd(Args a) {
;     extern __shared__ __attribute__((aligned(16))) unsigned char lds[];
	.amdhsa_kernel _Z8mega_fwd4Args
		.amdhsa_group_segment_fixed_size 0
		.amdhsa_private_segment_fixed_size 0
		.amdhsa_kernarg_size 416
		.amdhsa_user_sgpr_count 2
		.amdhsa_user_sgpr_dispatch_ptr 0
		.amdhsa_user_sgpr_queue_ptr 0
		.amdhsa_user_sgpr_kernarg_segment_ptr 1
		.amdhsa_user_sgpr_dispatch_id 0
		.amdhsa_user_sgpr_kernarg_preload_length 0
		.amdhsa_user_sgpr_kernarg_preload_offset 0
		.amdhsa_user_sgpr_private_segment_size 0
		.amdhsa_uses_dynamic_stack 0
		.amdhsa_enable_private_segment 0
		.amdhsa_system_sgpr_workgroup_id_x 1
		.amdhsa_system_sgpr_workgroup_id_y 0
		.amdhsa_system_sgpr_workgroup_id_z 0
		.amdhsa_system_sgpr_workgroup_info 0
		.amdhsa_system_vgpr_workitem_id 2
		.amdhsa_next_free_vgpr 252
		.amdhsa_next_free_sgpr 98
		.amdhsa_accum_offset 252
		.amdhsa_reserve_vcc 1
		.amdhsa_float_round_mode_32 0
		.amdhsa_float_round_mode_16_64 0
		.amdhsa_float_denorm_mode_32 3
		.amdhsa_float_denorm_mode_16_64 3
		.amdhsa_dx10_clamp 1
		.amdhsa_ieee_mode 1
		.amdhsa_fp16_overflow 0
		.amdhsa_tg_split 0
		.amdhsa_exception_fp_ieee_invalid_op 0
		.amdhsa_exception_fp_denorm_src 0
		.amdhsa_exception_fp_ieee_div_zero 0
		.amdhsa_exception_fp_ieee_overflow 0
		.amdhsa_exception_fp_ieee_underflow 0
		.amdhsa_exception_fp_ieee_inexact 0
		.amdhsa_exception_int_div_zero 0
	.end_amdhsa_kernel

; __global__ void __launch_bounds__(NWAVES * 64, 2) mega_fwd(Args a) {
;     extern __shared__ __attribute__((aligned(16))) unsigned char lds[];
amdhsa.kernels:
  - .agpr_count:     0
    .args:
      - .offset:         0
        .size:           160
        .value_kind:     by_value
      - .offset:         160
        .size:           4
        .value_kind:     hidden_block_count_x
      - .offset:         164
        .size:           4
        .value_kind:     hidden_block_count_y
      - .offset:         168
        .size:           4
        .value_kind:     hidden_block_count_z
      - .offset:         172
        .size:           2
        .value_kind:     hidden_group_size_x
      - .offset:         174
        .size:           2
        .value_kind:     hidden_group_size_y
      - .offset:         176
        .size:           2
        .value_kind:     hidden_group_size_z
      - .offset:         178
        .size:           2
        .value_kind:     hidden_remainder_x
      - .offset:         180
        .size:           2
        .value_kind:     hidden_remainder_y
      - .offset:         182
        .size:           2
        .value_kind:     hidden_remainder_z
      - .offset:         200
        .size:           8
        .value_kind:     hidden_global_offset_x
      - .offset:         208
        .size:           8
        .value_kind:     hidden_global_offset_y
      - .offset:         216
        .size:           8
        .value_kind:     hidden_global_offset_z
      - .offset:         224
        .size:           2
        .value_kind:     hidden_grid_dims
      - .offset:         248
        .size:           8
        .value_kind:     hidden_multigrid_sync_arg
      - .offset:         280
        .size:           4
        .value_kind:     hidden_dynamic_lds_size
    .group_segment_fixed_size: 0
    .kernarg_segment_align: 8
    .kernarg_segment_size: 416
    .language:       OpenCL C
    .language_version:
      - 2
      - 0
    .max_flat_workgroup_size: 512
    .name:           _Z8mega_fwd4Args
    .private_segment_fixed_size: 0
    .sgpr_count:     104
    .sgpr_spill_count: 79
    .symbol:         _Z8mega_fwd4Args.kd
    .uniform_work_group_size: 1
    .uses_dynamic_stack: false
    .vgpr_count:     252
    .vgpr_spill_count: 0
    .wavefront_size: 64
